# strategy 7.11: loop-control SALU block moved in front of the loop-back barrier in both GEMM K-loops (back-edge rotation)
# speedup vs baseline: 1.0022x; 1.0022x over previous
.LBB0_190:
	ds_read_b128 v[148:151], v157
	ds_read_b128 v[152:155], v157 offset:1024
	ds_read_b128 v[162:165], v157 offset:2048
	ds_read_b128 v[166:169], v157 offset:3072
	ds_read_b128 v[170:173], v158
	ds_read_b128 v[174:177], v158 offset:1024
	ds_read_b128 v[178:181], v158 offset:2048
	ds_read_b128 v[182:185], v158 offset:3072
	s_add_u32 s22, s20, 0xfffc0080
	s_addc_u32 s23, s21, -1
	s_cmp_eq_u32 s59, 12
	s_cselect_b32 s29, s5, s23
	s_cselect_b32 s28, s13, s22
	s_cselect_b32 s23, s11, s58
	s_cselect_b32 s22, s56, s57
	v_lshl_add_u64 v[218:219], s[20:21], 0, v[140:141]
	s_add_i32 m0, s19, 0xc000
	ds_read_b128 v[186:189], v159
	ds_read_b128 v[190:193], v159 offset:1024
	ds_read_b128 v[194:197], v159 offset:2048
	ds_read_b128 v[198:201], v159 offset:3072
	ds_read_b128 v[202:205], v159 offset:4096
	ds_read_b128 v[206:209], v159 offset:5120
	ds_read_b128 v[210:213], v159 offset:6144
	ds_read_b128 v[214:217], v159 offset:7168
	global_load_lds_dwordx4 v[218:219], off
	v_lshl_add_u64 v[218:219], s[20:21], 0, v[142:143]
	s_add_i32 m0, s19, 0xe000
	s_nop 0
	global_load_lds_dwordx4 v[218:219], off
	s_waitcnt vmcnt(8)
	s_waitcnt lgkmcnt(0)
	s_barrier
	s_setprio 1
	s_waitcnt lgkmcnt(0)
	v_mfma_f32_16x16x32_bf16 v[126:129], v[148:151], v[186:189], v[126:129]
	v_mfma_f32_16x16x32_bf16 v[122:125], v[162:165], v[186:189], v[122:125]
	v_mfma_f32_16x16x32_bf16 v[110:113], v[148:151], v[194:197], v[110:113]
	v_mfma_f32_16x16x32_bf16 v[106:109], v[162:165], v[194:197], v[106:109]
	v_mfma_f32_16x16x32_bf16 v[94:97], v[148:151], v[202:205], v[94:97]
	v_mfma_f32_16x16x32_bf16 v[90:93], v[162:165], v[202:205], v[90:93]
	v_mfma_f32_16x16x32_bf16 v[78:81], v[148:151], v[210:213], v[78:81]
	v_mfma_f32_16x16x32_bf16 v[74:77], v[162:165], v[210:213], v[74:77]
	v_mfma_f32_16x16x32_bf16 v[126:129], v[152:155], v[190:193], v[126:129]
	v_mfma_f32_16x16x32_bf16 v[122:125], v[166:169], v[190:193], v[122:125]
	v_mfma_f32_16x16x32_bf16 v[110:113], v[152:155], v[198:201], v[110:113]
	v_mfma_f32_16x16x32_bf16 v[106:109], v[166:169], v[198:201], v[106:109]
	v_mfma_f32_16x16x32_bf16 v[94:97], v[152:155], v[206:209], v[94:97]
	v_mfma_f32_16x16x32_bf16 v[90:93], v[166:169], v[206:209], v[90:93]
	v_mfma_f32_16x16x32_bf16 v[78:81], v[152:155], v[214:217], v[78:81]
	v_mfma_f32_16x16x32_bf16 v[74:77], v[166:169], v[214:217], v[74:77]
	s_setprio 0
	s_setprio 1
	v_mfma_f32_16x16x32_bf16 v[118:121], v[170:173], v[186:189], v[118:121]
	v_mfma_f32_16x16x32_bf16 v[114:117], v[178:181], v[186:189], v[114:117]
	v_mfma_f32_16x16x32_bf16 v[102:105], v[170:173], v[194:197], v[102:105]
	v_mfma_f32_16x16x32_bf16 v[98:101], v[178:181], v[194:197], v[98:101]
	v_mfma_f32_16x16x32_bf16 v[86:89], v[170:173], v[202:205], v[86:89]
	v_mfma_f32_16x16x32_bf16 v[82:85], v[178:181], v[202:205], v[82:85]
	v_mfma_f32_16x16x32_bf16 v[70:73], v[170:173], v[210:213], v[70:73]
	v_mfma_f32_16x16x32_bf16 v[66:69], v[178:181], v[210:213], v[66:69]
	v_mfma_f32_16x16x32_bf16 v[118:121], v[174:177], v[190:193], v[118:121]
	v_mfma_f32_16x16x32_bf16 v[114:117], v[182:185], v[190:193], v[114:117]
	v_mfma_f32_16x16x32_bf16 v[102:105], v[174:177], v[198:201], v[102:105]
	v_mfma_f32_16x16x32_bf16 v[98:101], v[182:185], v[198:201], v[98:101]
	v_mfma_f32_16x16x32_bf16 v[86:89], v[174:177], v[206:209], v[86:89]
	v_mfma_f32_16x16x32_bf16 v[82:85], v[182:185], v[206:209], v[82:85]
	v_mfma_f32_16x16x32_bf16 v[70:73], v[174:177], v[214:217], v[70:73]
	v_mfma_f32_16x16x32_bf16 v[66:69], v[182:185], v[214:217], v[66:69]
	s_setprio 0
	s_barrier
	s_add_i32 s60, s43, s33
	v_lshl_add_u64 v[218:219], s[22:23], 0, v[132:133]
	s_mov_b32 m0, s60
	ds_read_b128 v[186:189], v159 offset:16384
	ds_read_b128 v[190:193], v159 offset:17408
	ds_read_b128 v[194:197], v159 offset:18432
	ds_read_b128 v[198:201], v159 offset:19456
	ds_read_b128 v[202:205], v159 offset:20480
	ds_read_b128 v[206:209], v159 offset:21504
	ds_read_b128 v[210:213], v159 offset:22528
	ds_read_b128 v[214:217], v159 offset:23552
	global_load_lds_dwordx4 v[218:219], off
	s_add_i32 m0, s60, 0x2000
	s_add_u32 s60, s22, 0x40000
	v_lshl_add_u64 v[220:221], s[22:23], 0, v[136:137]
	s_addc_u32 s61, s23, 0
	s_add_i32 s62, s44, s33
	global_load_lds_dwordx4 v[220:221], off
	v_lshl_add_u64 v[222:223], s[60:61], 0, v[132:133]
	s_mov_b32 m0, s62
	v_lshl_add_u64 v[224:225], s[28:29], 0, v[134:135]
	global_load_lds_dwordx4 v[222:223], off
	v_lshl_add_u64 v[222:223], s[60:61], 0, v[136:137]
	s_add_i32 m0, s62, 0x2000
	s_nop 0
	global_load_lds_dwordx4 v[222:223], off
	v_lshl_add_u64 v[222:223], s[28:29], 0, v[130:131]
	s_mov_b32 m0, s19
	s_nop 0
	global_load_lds_dwordx4 v[222:223], off
	s_mov_b32 m0, s34
	s_nop 0
	global_load_lds_dwordx4 v[224:225], off
	s_waitcnt vmcnt(8)
	s_waitcnt lgkmcnt(0)
	s_barrier
	s_setprio 1
	s_waitcnt lgkmcnt(0)
	v_mfma_f32_16x16x32_bf16 v[62:65], v[148:151], v[186:189], v[62:65]
	v_mfma_f32_16x16x32_bf16 v[58:61], v[162:165], v[186:189], v[58:61]
	v_mfma_f32_16x16x32_bf16 v[46:49], v[148:151], v[194:197], v[46:49]
	v_mfma_f32_16x16x32_bf16 v[42:45], v[162:165], v[194:197], v[42:45]
	v_mfma_f32_16x16x32_bf16 v[30:33], v[148:151], v[202:205], v[30:33]
	v_mfma_f32_16x16x32_bf16 v[26:29], v[162:165], v[202:205], v[26:29]
	v_mfma_f32_16x16x32_bf16 v[14:17], v[148:151], v[210:213], v[14:17]
	v_mfma_f32_16x16x32_bf16 v[10:13], v[162:165], v[210:213], v[10:13]
	v_mfma_f32_16x16x32_bf16 v[62:65], v[152:155], v[190:193], v[62:65]
	v_mfma_f32_16x16x32_bf16 v[58:61], v[166:169], v[190:193], v[58:61]
	v_mfma_f32_16x16x32_bf16 v[46:49], v[152:155], v[198:201], v[46:49]
	v_mfma_f32_16x16x32_bf16 v[42:45], v[166:169], v[198:201], v[42:45]
	v_mfma_f32_16x16x32_bf16 v[30:33], v[152:155], v[206:209], v[30:33]
	v_mfma_f32_16x16x32_bf16 v[26:29], v[166:169], v[206:209], v[26:29]
	v_mfma_f32_16x16x32_bf16 v[14:17], v[152:155], v[214:217], v[14:17]
	v_mfma_f32_16x16x32_bf16 v[10:13], v[166:169], v[214:217], v[10:13]
	s_setprio 0
	s_setprio 1
	v_mfma_f32_16x16x32_bf16 v[54:57], v[170:173], v[186:189], v[54:57]
	v_mfma_f32_16x16x32_bf16 v[50:53], v[178:181], v[186:189], v[50:53]
	v_mfma_f32_16x16x32_bf16 v[38:41], v[170:173], v[194:197], v[38:41]
	v_mfma_f32_16x16x32_bf16 v[34:37], v[178:181], v[194:197], v[34:37]
	v_mfma_f32_16x16x32_bf16 v[22:25], v[170:173], v[202:205], v[22:25]
	v_mfma_f32_16x16x32_bf16 v[18:21], v[178:181], v[202:205], v[18:21]
	v_mfma_f32_16x16x32_bf16 v[6:9], v[170:173], v[210:213], v[6:9]
	v_mfma_f32_16x16x32_bf16 v[2:5], v[178:181], v[210:213], v[2:5]
	v_mfma_f32_16x16x32_bf16 v[54:57], v[174:177], v[190:193], v[54:57]
	v_mfma_f32_16x16x32_bf16 v[50:53], v[182:185], v[190:193], v[50:53]
	v_mfma_f32_16x16x32_bf16 v[38:41], v[174:177], v[198:201], v[38:41]
	v_mfma_f32_16x16x32_bf16 v[34:37], v[182:185], v[198:201], v[34:37]
	v_mfma_f32_16x16x32_bf16 v[22:25], v[174:177], v[206:209], v[22:25]
	v_mfma_f32_16x16x32_bf16 v[18:21], v[182:185], v[206:209], v[18:21]
	v_mfma_f32_16x16x32_bf16 v[6:9], v[174:177], v[214:217], v[6:9]
	v_mfma_f32_16x16x32_bf16 v[2:5], v[182:185], v[214:217], v[2:5]
	s_setprio 0
	s_barrier
	s_add_i32 s60, 0, 0x18000
	v_add_u32_e32 v138, s60, v156
	s_add_i32 s61, 0, 0x1c000
	ds_read_b128 v[148:151], v138
	ds_read_b128 v[152:155], v138 offset:1024
	ds_read_b128 v[162:165], v138 offset:2048
	ds_read_b128 v[166:169], v138 offset:3072
	v_add_u32_e32 v138, s61, v156
	ds_read_b128 v[170:173], v138
	ds_read_b128 v[174:177], v138 offset:1024
	ds_read_b128 v[178:181], v138 offset:2048
	ds_read_b128 v[182:185], v138 offset:3072
	s_add_u32 s28, s28, 0x40000
	s_addc_u32 s29, s29, 0
	s_mov_b32 m0, s35
	v_lshl_add_u64 v[226:227], s[28:29], 0, v[130:131]
	ds_read_b128 v[186:189], v159 offset:32768
	ds_read_b128 v[190:193], v159 offset:33792
	ds_read_b128 v[194:197], v159 offset:34816
	ds_read_b128 v[198:201], v159 offset:35840
	ds_read_b128 v[202:205], v159 offset:36864
	ds_read_b128 v[206:209], v159 offset:37888
	ds_read_b128 v[210:213], v159 offset:38912
	ds_read_b128 v[214:217], v159 offset:39936
	global_load_lds_dwordx4 v[226:227], off
	v_lshl_add_u64 v[226:227], s[28:29], 0, v[134:135]
	s_mov_b32 m0, s36
	s_nop 0
	global_load_lds_dwordx4 v[226:227], off
	s_waitcnt vmcnt(8)
	s_waitcnt lgkmcnt(0)
	s_barrier
	s_setprio 1
	s_waitcnt lgkmcnt(0)
	v_mfma_f32_16x16x32_bf16 v[126:129], v[148:151], v[186:189], v[126:129]
	v_mfma_f32_16x16x32_bf16 v[122:125], v[162:165], v[186:189], v[122:125]
	v_mfma_f32_16x16x32_bf16 v[110:113], v[148:151], v[194:197], v[110:113]
	v_mfma_f32_16x16x32_bf16 v[106:109], v[162:165], v[194:197], v[106:109]
	v_mfma_f32_16x16x32_bf16 v[94:97], v[148:151], v[202:205], v[94:97]
	v_mfma_f32_16x16x32_bf16 v[90:93], v[162:165], v[202:205], v[90:93]
	v_mfma_f32_16x16x32_bf16 v[78:81], v[148:151], v[210:213], v[78:81]
	v_mfma_f32_16x16x32_bf16 v[74:77], v[162:165], v[210:213], v[74:77]
	v_mfma_f32_16x16x32_bf16 v[126:129], v[152:155], v[190:193], v[126:129]
	v_mfma_f32_16x16x32_bf16 v[122:125], v[166:169], v[190:193], v[122:125]
	v_mfma_f32_16x16x32_bf16 v[110:113], v[152:155], v[198:201], v[110:113]
	v_mfma_f32_16x16x32_bf16 v[106:109], v[166:169], v[198:201], v[106:109]
	v_mfma_f32_16x16x32_bf16 v[94:97], v[152:155], v[206:209], v[94:97]
	v_mfma_f32_16x16x32_bf16 v[90:93], v[166:169], v[206:209], v[90:93]
	v_mfma_f32_16x16x32_bf16 v[78:81], v[152:155], v[214:217], v[78:81]
	v_mfma_f32_16x16x32_bf16 v[74:77], v[166:169], v[214:217], v[74:77]
	s_setprio 0
	s_setprio 1
	v_mfma_f32_16x16x32_bf16 v[118:121], v[170:173], v[186:189], v[118:121]
	v_mfma_f32_16x16x32_bf16 v[114:117], v[178:181], v[186:189], v[114:117]
	v_mfma_f32_16x16x32_bf16 v[102:105], v[170:173], v[194:197], v[102:105]
	v_mfma_f32_16x16x32_bf16 v[98:101], v[178:181], v[194:197], v[98:101]
	v_mfma_f32_16x16x32_bf16 v[86:89], v[170:173], v[202:205], v[86:89]
	v_mfma_f32_16x16x32_bf16 v[82:85], v[178:181], v[202:205], v[82:85]
	v_mfma_f32_16x16x32_bf16 v[70:73], v[170:173], v[210:213], v[70:73]
	v_mfma_f32_16x16x32_bf16 v[66:69], v[178:181], v[210:213], v[66:69]
	v_mfma_f32_16x16x32_bf16 v[118:121], v[174:177], v[190:193], v[118:121]
	v_mfma_f32_16x16x32_bf16 v[114:117], v[182:185], v[190:193], v[114:117]
	v_mfma_f32_16x16x32_bf16 v[102:105], v[174:177], v[198:201], v[102:105]
	v_mfma_f32_16x16x32_bf16 v[98:101], v[182:185], v[198:201], v[98:101]
	v_mfma_f32_16x16x32_bf16 v[86:89], v[174:177], v[206:209], v[86:89]
	v_mfma_f32_16x16x32_bf16 v[82:85], v[182:185], v[206:209], v[82:85]
	v_mfma_f32_16x16x32_bf16 v[70:73], v[174:177], v[214:217], v[70:73]
	v_mfma_f32_16x16x32_bf16 v[66:69], v[182:185], v[214:217], v[66:69]
	s_setprio 0
	s_barrier
	s_add_i32 s28, s60, s33
	v_lshl_add_u64 v[218:219], v[218:219], 0, s[6:7]
	s_mov_b32 m0, s28
	ds_read_b128 v[186:189], v159 offset:49152
	ds_read_b128 v[190:193], v159 offset:50176
	ds_read_b128 v[194:197], v159 offset:51200
	ds_read_b128 v[198:201], v159 offset:52224
	ds_read_b128 v[202:205], v159 offset:53248
	ds_read_b128 v[206:209], v159 offset:54272
	ds_read_b128 v[210:213], v159 offset:55296
	ds_read_b128 v[214:217], v159 offset:56320
	global_load_lds_dwordx4 v[218:219], off
	s_add_i32 m0, s28, 0x2000
	s_add_u32 s22, s22, 0x40080
	v_lshl_add_u64 v[218:219], v[220:221], 0, s[6:7]
	s_addc_u32 s23, s23, 0
	s_add_i32 s28, s61, s33
	global_load_lds_dwordx4 v[218:219], off
	v_lshl_add_u64 v[218:219], s[22:23], 0, v[132:133]
	s_mov_b32 m0, s28
	s_nop 0
	global_load_lds_dwordx4 v[218:219], off
	v_lshl_add_u64 v[218:219], s[22:23], 0, v[136:137]
	s_add_i32 m0, s28, 0x2000
	s_nop 0
	global_load_lds_dwordx4 v[218:219], off
	v_lshl_add_u64 v[218:219], v[222:223], 0, s[6:7]
	s_mov_b32 m0, s39
	s_nop 0
	global_load_lds_dwordx4 v[218:219], off
	v_lshl_add_u64 v[218:219], v[224:225], 0, s[6:7]
	s_mov_b32 m0, s40
	s_nop 0
	global_load_lds_dwordx4 v[218:219], off
	s_waitcnt vmcnt(8)
	s_waitcnt lgkmcnt(0)
	s_barrier
	s_setprio 1
	s_waitcnt lgkmcnt(0)
	v_mfma_f32_16x16x32_bf16 v[62:65], v[148:151], v[186:189], v[62:65]
	v_mfma_f32_16x16x32_bf16 v[58:61], v[162:165], v[186:189], v[58:61]
	v_mfma_f32_16x16x32_bf16 v[46:49], v[148:151], v[194:197], v[46:49]
	v_mfma_f32_16x16x32_bf16 v[42:45], v[162:165], v[194:197], v[42:45]
	v_mfma_f32_16x16x32_bf16 v[30:33], v[148:151], v[202:205], v[30:33]
	v_mfma_f32_16x16x32_bf16 v[26:29], v[162:165], v[202:205], v[26:29]
	v_mfma_f32_16x16x32_bf16 v[14:17], v[148:151], v[210:213], v[14:17]
	v_mfma_f32_16x16x32_bf16 v[10:13], v[162:165], v[210:213], v[10:13]
	v_mfma_f32_16x16x32_bf16 v[62:65], v[152:155], v[190:193], v[62:65]
	v_mfma_f32_16x16x32_bf16 v[58:61], v[166:169], v[190:193], v[58:61]
	v_mfma_f32_16x16x32_bf16 v[46:49], v[152:155], v[198:201], v[46:49]
	v_mfma_f32_16x16x32_bf16 v[42:45], v[166:169], v[198:201], v[42:45]
	v_mfma_f32_16x16x32_bf16 v[30:33], v[152:155], v[206:209], v[30:33]
	v_mfma_f32_16x16x32_bf16 v[26:29], v[166:169], v[206:209], v[26:29]
	v_mfma_f32_16x16x32_bf16 v[14:17], v[152:155], v[214:217], v[14:17]
	v_mfma_f32_16x16x32_bf16 v[10:13], v[166:169], v[214:217], v[10:13]
	s_setprio 0
	s_setprio 1
	v_mfma_f32_16x16x32_bf16 v[54:57], v[170:173], v[186:189], v[54:57]
	v_mfma_f32_16x16x32_bf16 v[50:53], v[178:181], v[186:189], v[50:53]
	v_mfma_f32_16x16x32_bf16 v[38:41], v[170:173], v[194:197], v[38:41]
	v_mfma_f32_16x16x32_bf16 v[34:37], v[178:181], v[194:197], v[34:37]
	v_mfma_f32_16x16x32_bf16 v[22:25], v[170:173], v[202:205], v[22:25]
	v_mfma_f32_16x16x32_bf16 v[18:21], v[178:181], v[202:205], v[18:21]
	v_mfma_f32_16x16x32_bf16 v[6:9], v[170:173], v[210:213], v[6:9]
	v_mfma_f32_16x16x32_bf16 v[2:5], v[178:181], v[210:213], v[2:5]
	v_mfma_f32_16x16x32_bf16 v[54:57], v[174:177], v[190:193], v[54:57]
	v_mfma_f32_16x16x32_bf16 v[50:53], v[182:185], v[190:193], v[50:53]
	v_mfma_f32_16x16x32_bf16 v[38:41], v[174:177], v[198:201], v[38:41]
	v_mfma_f32_16x16x32_bf16 v[34:37], v[182:185], v[198:201], v[34:37]
	v_mfma_f32_16x16x32_bf16 v[22:25], v[174:177], v[206:209], v[22:25]
	v_mfma_f32_16x16x32_bf16 v[18:21], v[182:185], v[206:209], v[18:21]
	v_mfma_f32_16x16x32_bf16 v[6:9], v[174:177], v[214:217], v[6:9]
	v_mfma_f32_16x16x32_bf16 v[2:5], v[182:185], v[214:217], v[2:5]
	s_setprio 0
	s_add_i32 s59, s59, 2
	s_add_u32 s20, s20, 0x100
	s_addc_u32 s21, s21, 0
	s_add_u32 s57, s57, 0x100
	s_addc_u32 s58, s58, 0
	s_cmp_gt_u32 s59, 13
	s_barrier
	s_cbranch_scc0 .LBB0_190
	s_and_b64 vcc, exec, s[8:9]
	s_cbranch_vccz .LBB0_193
	s_barrier

.LBB0_920:
	ds_read_b128 v[148:151], v142 offset:3072
	ds_read_b128 v[152:155], v142 offset:2048
	ds_read_b128 v[156:159], v142 offset:1024
	ds_read_b128 v[160:163], v142
	ds_read_b128 v[166:169], v143 offset:3072
	ds_read_b128 v[170:173], v143 offset:2048
	ds_read_b128 v[174:177], v143 offset:1024
	ds_read_b128 v[178:181], v143
	s_add_u32 s12, s82, s27
	s_addc_u32 s13, s83, s28
	s_add_u32 s14, s82, s25
	s_addc_u32 s15, s83, s26
	s_cmp_eq_u32 s29, 12
	s_cselect_b32 s16, s0, s12
	s_cselect_b32 s17, s1, s13
	s_cselect_b32 s15, s3, s15
	s_cselect_b32 s14, s2, s14
	s_add_u32 s12, s16, 0x200000
	s_addc_u32 s13, s17, 0
	s_mov_b32 m0, s30
	v_lshl_add_u64 v[214:215], s[82:83], 0, v[138:139]
	ds_read_b128 v[182:185], v144
	ds_read_b128 v[186:189], v144 offset:1024
	ds_read_b128 v[190:193], v144 offset:2048
	ds_read_b128 v[194:197], v144 offset:3072
	ds_read_b128 v[198:201], v144 offset:4096
	ds_read_b128 v[202:205], v144 offset:5120
	ds_read_b128 v[206:209], v144 offset:6144
	ds_read_b128 v[210:213], v144 offset:7168
	global_load_lds_dwordx4 v[214:215], off
	v_lshl_add_u64 v[214:215], s[82:83], 0, v[140:141]
	s_mov_b32 m0, s31
	s_nop 0
	global_load_lds_dwordx4 v[214:215], off
	s_waitcnt vmcnt(8)
	s_waitcnt lgkmcnt(0)
	s_barrier
	s_setprio 1
	s_waitcnt lgkmcnt(0)
	v_mfma_f32_16x16x32_bf16 v[66:69], v[178:181], v[182:185], v[66:69]
	v_mfma_f32_16x16x32_bf16 v[38:41], v[170:173], v[182:185], v[38:41]
	v_mfma_f32_16x16x32_bf16 v[78:81], v[178:181], v[190:193], v[78:81]
	v_mfma_f32_16x16x32_bf16 v[46:49], v[170:173], v[190:193], v[46:49]
	v_mfma_f32_16x16x32_bf16 v[90:93], v[178:181], v[198:201], v[90:93]
	v_mfma_f32_16x16x32_bf16 v[58:61], v[170:173], v[198:201], v[58:61]
	v_mfma_f32_16x16x32_bf16 v[102:105], v[178:181], v[206:209], v[102:105]
	v_mfma_f32_16x16x32_bf16 v[70:73], v[170:173], v[206:209], v[70:73]
	v_mfma_f32_16x16x32_bf16 v[66:69], v[174:177], v[186:189], v[66:69]
	v_mfma_f32_16x16x32_bf16 v[38:41], v[166:169], v[186:189], v[38:41]
	v_mfma_f32_16x16x32_bf16 v[78:81], v[174:177], v[194:197], v[78:81]
	v_mfma_f32_16x16x32_bf16 v[46:49], v[166:169], v[194:197], v[46:49]
	v_mfma_f32_16x16x32_bf16 v[90:93], v[174:177], v[202:205], v[90:93]
	v_mfma_f32_16x16x32_bf16 v[58:61], v[166:169], v[202:205], v[58:61]
	v_mfma_f32_16x16x32_bf16 v[102:105], v[174:177], v[210:213], v[102:105]
	v_mfma_f32_16x16x32_bf16 v[70:73], v[166:169], v[210:213], v[70:73]
	s_setprio 0
	s_setprio 1
	v_mfma_f32_16x16x32_bf16 v[14:17], v[160:163], v[182:185], v[14:17]
	v_mfma_f32_16x16x32_bf16 v[2:5], v[152:155], v[182:185], v[2:5]
	v_mfma_f32_16x16x32_bf16 v[22:25], v[160:163], v[190:193], v[22:25]
	v_mfma_f32_16x16x32_bf16 v[6:9], v[152:155], v[190:193], v[6:9]
	v_mfma_f32_16x16x32_bf16 v[30:33], v[160:163], v[198:201], v[30:33]
	v_mfma_f32_16x16x32_bf16 v[10:13], v[152:155], v[198:201], v[10:13]
	v_mfma_f32_16x16x32_bf16 v[42:45], v[160:163], v[206:209], v[42:45]
	v_mfma_f32_16x16x32_bf16 v[18:21], v[152:155], v[206:209], v[18:21]
	v_mfma_f32_16x16x32_bf16 v[14:17], v[156:159], v[186:189], v[14:17]
	v_mfma_f32_16x16x32_bf16 v[2:5], v[148:151], v[186:189], v[2:5]
	v_mfma_f32_16x16x32_bf16 v[22:25], v[156:159], v[194:197], v[22:25]
	v_mfma_f32_16x16x32_bf16 v[6:9], v[148:151], v[194:197], v[6:9]
	v_mfma_f32_16x16x32_bf16 v[30:33], v[156:159], v[202:205], v[30:33]
	v_mfma_f32_16x16x32_bf16 v[10:13], v[148:151], v[202:205], v[10:13]
	v_mfma_f32_16x16x32_bf16 v[42:45], v[156:159], v[210:213], v[42:45]
	v_mfma_f32_16x16x32_bf16 v[18:21], v[148:151], v[210:213], v[18:21]
	s_setprio 0
	s_barrier
	s_mov_b32 m0, s33
	v_lshl_add_u64 v[214:215], s[14:15], 0, v[132:133]
	s_add_u32 s42, s14, 0x40000
	ds_read_b128 v[182:185], v144 offset:16384
	ds_read_b128 v[186:189], v144 offset:17408
	ds_read_b128 v[190:193], v144 offset:18432
	ds_read_b128 v[194:197], v144 offset:19456
	ds_read_b128 v[198:201], v144 offset:20480
	ds_read_b128 v[202:205], v144 offset:21504
	ds_read_b128 v[206:209], v144 offset:22528
	ds_read_b128 v[210:213], v144 offset:23552
	global_load_lds_dwordx4 v[214:215], off
	v_lshl_add_u64 v[216:217], s[14:15], 0, v[136:137]
	s_mov_b32 m0, s34
	s_addc_u32 s43, s15, 0
	global_load_lds_dwordx4 v[216:217], off
	v_lshl_add_u64 v[218:219], s[42:43], 0, v[132:133]
	s_mov_b32 m0, s35
	s_nop 0
	global_load_lds_dwordx4 v[218:219], off
	v_lshl_add_u64 v[218:219], s[42:43], 0, v[136:137]
	s_mov_b32 m0, s36
	s_nop 0
	global_load_lds_dwordx4 v[218:219], off
	v_lshl_add_u64 v[218:219], s[16:17], 0, v[130:131]
	s_mov_b32 m0, s7
	s_nop 0
	global_load_lds_dwordx4 v[218:219], off
	v_lshl_add_u64 v[218:219], s[16:17], 0, v[134:135]
	s_mov_b32 m0, s20
	s_nop 0
	global_load_lds_dwordx4 v[218:219], off
	s_waitcnt vmcnt(8)
	s_waitcnt lgkmcnt(0)
	s_barrier
	s_setprio 1
	s_waitcnt lgkmcnt(0)
	v_mfma_f32_16x16x32_bf16 v[106:109], v[178:181], v[182:185], v[106:109]
	v_mfma_f32_16x16x32_bf16 v[82:85], v[170:173], v[182:185], v[82:85]
	v_mfma_f32_16x16x32_bf16 v[118:121], v[178:181], v[190:193], v[118:121]
	v_mfma_f32_16x16x32_bf16 v[94:97], v[170:173], v[190:193], v[94:97]
	v_mfma_f32_16x16x32_bf16 v[126:129], v[178:181], v[198:201], v[126:129]
	v_mfma_f32_16x16x32_bf16 v[110:113], v[170:173], v[198:201], v[110:113]
	v_mfma_f32_16x16x32_bf16 v[122:125], v[178:181], v[206:209], v[122:125]
	v_mfma_f32_16x16x32_bf16 v[114:117], v[170:173], v[206:209], v[114:117]
	v_mfma_f32_16x16x32_bf16 v[106:109], v[174:177], v[186:189], v[106:109]
	v_mfma_f32_16x16x32_bf16 v[82:85], v[166:169], v[186:189], v[82:85]
	v_mfma_f32_16x16x32_bf16 v[118:121], v[174:177], v[194:197], v[118:121]
	v_mfma_f32_16x16x32_bf16 v[94:97], v[166:169], v[194:197], v[94:97]
	v_mfma_f32_16x16x32_bf16 v[126:129], v[174:177], v[202:205], v[126:129]
	v_mfma_f32_16x16x32_bf16 v[110:113], v[166:169], v[202:205], v[110:113]
	v_mfma_f32_16x16x32_bf16 v[122:125], v[174:177], v[210:213], v[122:125]
	v_mfma_f32_16x16x32_bf16 v[114:117], v[166:169], v[210:213], v[114:117]
	s_setprio 0
	s_setprio 1
	v_mfma_f32_16x16x32_bf16 v[50:53], v[160:163], v[182:185], v[50:53]
	v_mfma_f32_16x16x32_bf16 v[26:29], v[152:155], v[182:185], v[26:29]
	v_mfma_f32_16x16x32_bf16 v[62:65], v[160:163], v[190:193], v[62:65]
	v_mfma_f32_16x16x32_bf16 v[34:37], v[152:155], v[190:193], v[34:37]
	v_mfma_f32_16x16x32_bf16 v[86:89], v[160:163], v[198:201], v[86:89]
	v_mfma_f32_16x16x32_bf16 v[54:57], v[152:155], v[198:201], v[54:57]
	v_mfma_f32_16x16x32_bf16 v[98:101], v[160:163], v[206:209], v[98:101]
	v_mfma_f32_16x16x32_bf16 v[74:77], v[152:155], v[206:209], v[74:77]
	v_mfma_f32_16x16x32_bf16 v[50:53], v[156:159], v[186:189], v[50:53]
	v_mfma_f32_16x16x32_bf16 v[26:29], v[148:151], v[186:189], v[26:29]
	v_mfma_f32_16x16x32_bf16 v[62:65], v[156:159], v[194:197], v[62:65]
	v_mfma_f32_16x16x32_bf16 v[34:37], v[148:151], v[194:197], v[34:37]
	v_mfma_f32_16x16x32_bf16 v[86:89], v[156:159], v[202:205], v[86:89]
	v_mfma_f32_16x16x32_bf16 v[54:57], v[148:151], v[202:205], v[54:57]
	v_mfma_f32_16x16x32_bf16 v[98:101], v[156:159], v[210:213], v[98:101]
	v_mfma_f32_16x16x32_bf16 v[74:77], v[148:151], v[210:213], v[74:77]
	s_setprio 0
	s_barrier
	ds_read_b128 v[148:151], v145
	ds_read_b128 v[152:155], v145 offset:1024
	ds_read_b128 v[156:159], v145 offset:2048
	ds_read_b128 v[160:163], v145 offset:3072
	ds_read_b128 v[166:169], v146
	ds_read_b128 v[170:173], v146 offset:1024
	ds_read_b128 v[174:177], v146 offset:2048
	ds_read_b128 v[178:181], v146 offset:3072
	s_add_u32 s16, s16, 0x4000
	s_addc_u32 s17, s17, 0
	s_mov_b32 m0, s21
	v_lshl_add_u64 v[218:219], s[16:17], 0, v[130:131]
	ds_read_b128 v[182:185], v144 offset:32768
	ds_read_b128 v[186:189], v144 offset:33792
	ds_read_b128 v[190:193], v144 offset:34816
	ds_read_b128 v[194:197], v144 offset:35840
	ds_read_b128 v[198:201], v144 offset:36864
	ds_read_b128 v[202:205], v144 offset:37888
	ds_read_b128 v[206:209], v144 offset:38912
	ds_read_b128 v[210:213], v144 offset:39936
	global_load_lds_dwordx4 v[218:219], off
	v_lshl_add_u64 v[218:219], s[16:17], 0, v[134:135]
	s_mov_b32 m0, s22
	s_nop 0
	global_load_lds_dwordx4 v[218:219], off
	s_waitcnt vmcnt(8)
	s_waitcnt lgkmcnt(0)
	s_barrier
	s_setprio 1
	s_waitcnt lgkmcnt(0)
	v_mfma_f32_16x16x32_bf16 v[66:69], v[148:151], v[182:185], v[66:69]
	v_mfma_f32_16x16x32_bf16 v[38:41], v[156:159], v[182:185], v[38:41]
	v_mfma_f32_16x16x32_bf16 v[78:81], v[148:151], v[190:193], v[78:81]
	v_mfma_f32_16x16x32_bf16 v[46:49], v[156:159], v[190:193], v[46:49]
	v_mfma_f32_16x16x32_bf16 v[90:93], v[148:151], v[198:201], v[90:93]
	v_mfma_f32_16x16x32_bf16 v[58:61], v[156:159], v[198:201], v[58:61]
	v_mfma_f32_16x16x32_bf16 v[102:105], v[148:151], v[206:209], v[102:105]
	v_mfma_f32_16x16x32_bf16 v[70:73], v[156:159], v[206:209], v[70:73]
	v_mfma_f32_16x16x32_bf16 v[66:69], v[152:155], v[186:189], v[66:69]
	v_mfma_f32_16x16x32_bf16 v[38:41], v[160:163], v[186:189], v[38:41]
	v_mfma_f32_16x16x32_bf16 v[78:81], v[152:155], v[194:197], v[78:81]
	v_mfma_f32_16x16x32_bf16 v[46:49], v[160:163], v[194:197], v[46:49]
	v_mfma_f32_16x16x32_bf16 v[90:93], v[152:155], v[202:205], v[90:93]
	v_mfma_f32_16x16x32_bf16 v[58:61], v[160:163], v[202:205], v[58:61]
	v_mfma_f32_16x16x32_bf16 v[102:105], v[152:155], v[210:213], v[102:105]
	v_mfma_f32_16x16x32_bf16 v[70:73], v[160:163], v[210:213], v[70:73]
	s_setprio 0
	s_setprio 1
	v_mfma_f32_16x16x32_bf16 v[14:17], v[166:169], v[182:185], v[14:17]
	v_mfma_f32_16x16x32_bf16 v[2:5], v[174:177], v[182:185], v[2:5]
	v_mfma_f32_16x16x32_bf16 v[22:25], v[166:169], v[190:193], v[22:25]
	v_mfma_f32_16x16x32_bf16 v[6:9], v[174:177], v[190:193], v[6:9]
	v_mfma_f32_16x16x32_bf16 v[30:33], v[166:169], v[198:201], v[30:33]
	v_mfma_f32_16x16x32_bf16 v[10:13], v[174:177], v[198:201], v[10:13]
	v_mfma_f32_16x16x32_bf16 v[42:45], v[166:169], v[206:209], v[42:45]
	v_mfma_f32_16x16x32_bf16 v[18:21], v[174:177], v[206:209], v[18:21]
	v_mfma_f32_16x16x32_bf16 v[14:17], v[170:173], v[186:189], v[14:17]
	v_mfma_f32_16x16x32_bf16 v[2:5], v[178:181], v[186:189], v[2:5]
	v_mfma_f32_16x16x32_bf16 v[22:25], v[170:173], v[194:197], v[22:25]
	v_mfma_f32_16x16x32_bf16 v[6:9], v[178:181], v[194:197], v[6:9]
	v_mfma_f32_16x16x32_bf16 v[30:33], v[170:173], v[202:205], v[30:33]
	v_mfma_f32_16x16x32_bf16 v[10:13], v[178:181], v[202:205], v[10:13]
	v_mfma_f32_16x16x32_bf16 v[42:45], v[170:173], v[210:213], v[42:45]
	v_mfma_f32_16x16x32_bf16 v[18:21], v[178:181], v[210:213], v[18:21]
	s_setprio 0
	s_barrier
	s_mov_b32 m0, s37
	v_lshl_add_u64 v[214:215], v[214:215], 0, s[4:5]
	s_add_u32 s14, s14, 0x40080
	ds_read_b128 v[182:185], v144 offset:49152
	ds_read_b128 v[186:189], v144 offset:50176
	ds_read_b128 v[190:193], v144 offset:51200
	ds_read_b128 v[194:197], v144 offset:52224
	ds_read_b128 v[198:201], v144 offset:53248
	ds_read_b128 v[202:205], v144 offset:54272
	ds_read_b128 v[206:209], v144 offset:55296
	ds_read_b128 v[210:213], v144 offset:56320
	global_load_lds_dwordx4 v[214:215], off
	v_lshl_add_u64 v[214:215], v[216:217], 0, s[4:5]
	s_mov_b32 m0, s38
	s_addc_u32 s15, s15, 0
	global_load_lds_dwordx4 v[214:215], off
	v_lshl_add_u64 v[214:215], s[14:15], 0, v[132:133]
	s_mov_b32 m0, s39
	s_nop 0
	global_load_lds_dwordx4 v[214:215], off
	v_lshl_add_u64 v[214:215], s[14:15], 0, v[136:137]
	s_mov_b32 m0, s40
	s_nop 0
	global_load_lds_dwordx4 v[214:215], off
	v_lshl_add_u64 v[214:215], s[12:13], 0, v[130:131]
	s_mov_b32 m0, s23
	s_nop 0
	global_load_lds_dwordx4 v[214:215], off
	v_lshl_add_u64 v[214:215], s[12:13], 0, v[134:135]
	s_mov_b32 m0, s24
	s_nop 0
	global_load_lds_dwordx4 v[214:215], off
	s_waitcnt vmcnt(8)
	s_waitcnt lgkmcnt(0)
	s_barrier
	s_setprio 1
	s_waitcnt lgkmcnt(0)
	v_mfma_f32_16x16x32_bf16 v[106:109], v[148:151], v[182:185], v[106:109]
	v_mfma_f32_16x16x32_bf16 v[82:85], v[156:159], v[182:185], v[82:85]
	v_mfma_f32_16x16x32_bf16 v[118:121], v[148:151], v[190:193], v[118:121]
	v_mfma_f32_16x16x32_bf16 v[94:97], v[156:159], v[190:193], v[94:97]
	v_mfma_f32_16x16x32_bf16 v[126:129], v[148:151], v[198:201], v[126:129]
	v_mfma_f32_16x16x32_bf16 v[110:113], v[156:159], v[198:201], v[110:113]
	v_mfma_f32_16x16x32_bf16 v[122:125], v[148:151], v[206:209], v[122:125]
	v_mfma_f32_16x16x32_bf16 v[114:117], v[156:159], v[206:209], v[114:117]
	v_mfma_f32_16x16x32_bf16 v[106:109], v[152:155], v[186:189], v[106:109]
	v_mfma_f32_16x16x32_bf16 v[82:85], v[160:163], v[186:189], v[82:85]
	v_mfma_f32_16x16x32_bf16 v[118:121], v[152:155], v[194:197], v[118:121]
	v_mfma_f32_16x16x32_bf16 v[94:97], v[160:163], v[194:197], v[94:97]
	v_mfma_f32_16x16x32_bf16 v[126:129], v[152:155], v[202:205], v[126:129]
	v_mfma_f32_16x16x32_bf16 v[110:113], v[160:163], v[202:205], v[110:113]
	v_mfma_f32_16x16x32_bf16 v[122:125], v[152:155], v[210:213], v[122:125]
	v_mfma_f32_16x16x32_bf16 v[114:117], v[160:163], v[210:213], v[114:117]
	s_setprio 0
	s_setprio 1
	v_mfma_f32_16x16x32_bf16 v[50:53], v[166:169], v[182:185], v[50:53]
	v_mfma_f32_16x16x32_bf16 v[26:29], v[174:177], v[182:185], v[26:29]
	v_mfma_f32_16x16x32_bf16 v[62:65], v[166:169], v[190:193], v[62:65]
	v_mfma_f32_16x16x32_bf16 v[34:37], v[174:177], v[190:193], v[34:37]
	v_mfma_f32_16x16x32_bf16 v[86:89], v[166:169], v[198:201], v[86:89]
	v_mfma_f32_16x16x32_bf16 v[54:57], v[174:177], v[198:201], v[54:57]
	v_mfma_f32_16x16x32_bf16 v[98:101], v[166:169], v[206:209], v[98:101]
	v_mfma_f32_16x16x32_bf16 v[74:77], v[174:177], v[206:209], v[74:77]
	v_mfma_f32_16x16x32_bf16 v[50:53], v[170:173], v[186:189], v[50:53]
	v_mfma_f32_16x16x32_bf16 v[26:29], v[178:181], v[186:189], v[26:29]
	v_mfma_f32_16x16x32_bf16 v[62:65], v[170:173], v[194:197], v[62:65]
	v_mfma_f32_16x16x32_bf16 v[34:37], v[178:181], v[194:197], v[34:37]
	v_mfma_f32_16x16x32_bf16 v[86:89], v[170:173], v[202:205], v[86:89]
	v_mfma_f32_16x16x32_bf16 v[54:57], v[178:181], v[202:205], v[54:57]
	v_mfma_f32_16x16x32_bf16 v[98:101], v[170:173], v[210:213], v[98:101]
	v_mfma_f32_16x16x32_bf16 v[74:77], v[178:181], v[210:213], v[74:77]
	s_setprio 0
	s_add_i32 s29, s29, 2
	s_add_u32 s25, s25, 0x100
	s_addc_u32 s26, s26, 0
	s_add_u32 s27, s27, 0x400000
	s_addc_u32 s28, s28, 0
	v_lshl_add_u64 v[138:139], v[138:139], 0, s[10:11]
	s_cmp_lt_u32 s29, 14
	v_lshl_add_u64 v[140:141], v[140:141], 0, s[10:11]
	s_barrier
	s_cbranch_scc1 .LBB0_920
	s_waitcnt vmcnt(0)
	s_cmpk_gt_u32 s19, 0xff
	s_cbranch_scc1 .LBB0_923
	s_barrier
